# k34 + static s_setprio 1 for waves 4-7 also in the P7 gated up-projection GEMM (the one GEMM phase that had none)
# baseline (speedup 1.0000x reference)
; #define PG8_STAGE(bufoff, gbase, voff) do { _Pragma("unroll") for (int _i = 0; _i < 2; ++_i) \
;         __builtin_amdgcn_global_load_lds((const unsigned*)((const char*)(gbase) + (voff)[_i]), (LAS unsigned*)(lds + (bufoff) + ldsw + _i * 8192), 16, 0, 0); } while (0)
; #define PG8_BAR __builtin_amdgcn_s_barrier()
; template <class Epi, bool ALIGN_EPI, class Hook = NoHook>
; __device__ __forceinline__ void gemm_phase(LAS unsigned char* lds, const Gemm g, const StaticOrder& S, const Epi& E, const Hook& HK = Hook()) {
;     ...
;     for (int i = 0; i < 2; ++i) { int R, C; stage_rc(tid * 16 + i * 8192, R, C); const int Rb = Epi::PERM ? ((R & ~31) + perm32(R & 31)) : R;
;         voffA[i] = (unsigned)(R * g.lda + C) * 2u; voffB[i] = (unsigned)(Rb * g.ldb + C) * 2u; }
;     const size_t kstep = (size_t)(BK * 2);
;     const size_t hstepA = (size_t)HALF * g.lda * 2, hstepB = (size_t)HALF * g.ldb * 2;
;     const size_t tstepA = 2 * hstepA, tstepB = 2 * hstepB;
;     const unsigned ldsw = (unsigned)wid * 1024u;
;     const int aoff = lds_byte(wr * 64 + fr, fq * 8), boff = lds_byte(wc * 32 + fr, fq * 8);
;     ...
;     Unit cur, nxt; int ui = 0;
;     if (!S.next(0, cur)) return;
;     f32x4 acc[2][2][4][2];
; #pragma unroll
;     for (int a = 0; a < 2; ++a)
; #pragma unroll
;         for (int b = 0; b < 2; ++b)
; #pragma unroll
;             for (int m = 0; m < 4; ++m)
; #pragma unroll
;                 for (int n = 0; n < 2; ++n) acc[a][b][m][n] = (f32x4){0.f, 0.f, 0.f, 0.f};
;     bf16x8 At[4][2], B0[2][2], B1[2][2];
;     const char* cA = (const char*)g.A + (size_t)cur.pm * tstepA; const char* cB = (const char*)g.Bt + (size_t)cur.pn * tstepB;
;     PG8_STAGE(PG8_SB(0, 0), cB, voffB); PG8_STAGE(PG8_SB(0, 1), cB + hstepB, voffB); PG8_STAGE(PG8_SA(0, 0), cA, voffA); PG8_STAGE(PG8_SA(0, 1), cA + hstepA, voffA);
;     if (wr == 1) PG8_BAR;
.LBB0_696:
	v_ashrrev_i32_e32 v2, 31, v1
	v_lshrrev_b32_e32 v2, 26, v2
	v_add_u32_e32 v2, v1, v2
	v_ashrrev_i32_e32 v10, 6, v2
	v_bfe_i32 v2, v1, 27, 1
	v_lshlrev_b32_e32 v0, 4, v1
	v_lshrrev_b32_e32 v2, 22, v2
	v_add_u32_e32 v2, v0, v2
	v_and_b32_e32 v2, 0xfffffc00, v2
	v_sub_u32_e32 v2, v0, v2
	v_lshrrev_b32_e32 v3, 4, v2
	v_bitop3_b32 v2, v3, v2, 32 bitop3:0x6c
	v_ashrrev_i32_e32 v4, 31, v2
	v_lshrrev_b32_e32 v4, 26, v4
	v_add_u32_e32 v4, v2, v4
	v_lshlrev_b32_e32 v3, 3, v10
	v_ashrrev_i32_e32 v11, 6, v4
	v_and_b32_e32 v4, 0xc0, v4
	v_and_b32_e32 v3, -16, v3
	v_sub_u32_e32 v2, v2, v4
	v_mov_b32_e32 v4, 1
	v_add_u32_e32 v3, v11, v3
	v_ashrrev_i16_sdwa v2, v4, sext(v2) dst_sel:DWORD dst_unused:UNUSED_PAD src0_sel:DWORD src1_sel:BYTE_0
	v_lshlrev_b32_e32 v5, 5, v10
	v_bfe_i32 v12, v2, 0, 16
	v_lshlrev_b32_e32 v2, 1, v3
	v_lshrrev_b32_e32 v6, 2, v3
	v_and_b32_e32 v7, 3, v11
	s_mov_b32 s1, 0xfffe0
	v_and_b32_e32 v5, 32, v5
	v_and_b32_e32 v2, 24, v2
	v_and_b32_e32 v6, 4, v6
	v_and_or_b32 v7, v3, s1, v7
	v_or3_b32 v2, v7, v6, v2
	v_add_lshl_u32 v5, v5, v12, 1
	v_add_u32_e32 v0, 0x2000, v0
	v_lshl_add_u32 v134, v2, 12, v5
	v_ashrrev_i32_e32 v2, 31, v0
	v_lshrrev_b32_e32 v2, 22, v2
	v_add_u32_e32 v2, v0, v2
	v_ashrrev_i32_e32 v13, 10, v2
	v_mul_i32_i24_e32 v2, 0x400, v13
	v_sub_u32_e32 v0, v0, v2
	v_lshrrev_b32_e32 v2, 4, v0
	v_bitop3_b32 v0, v2, v0, 32 bitop3:0x6c
	v_lshl_add_u32 v132, v3, 12, v5
	v_ashrrev_i32_e32 v3, 31, v0
	v_lshrrev_b32_e32 v3, 26, v3
	v_add_u32_e32 v3, v0, v3
	v_lshlrev_b32_e32 v2, 3, v13
	v_ashrrev_i32_e32 v14, 6, v3
	v_and_b32_e32 v3, 0xc0, v3
	s_ashr_i32 s0, s8, 3
	v_and_b32_e32 v2, -16, v2
	v_sub_u32_e32 v0, v0, v3
	v_add_u32_e32 v2, v14, v2
	v_ashrrev_i16_sdwa v0, v4, sext(v0) dst_sel:DWORD dst_unused:UNUSED_PAD src0_sel:DWORD src1_sel:BYTE_0
	v_and_b32_e32 v4, 3, v14
	s_add_i32 s0, s6, s0
	v_and_or_b32 v4, v2, s1, v4
	s_ashr_i32 s1, s0, 31
	s_lshr_b32 s1, s1, 27
	s_add_i32 s1, s0, s1
	s_ashr_i32 s6, s1, 5
	s_andn2_b32 s1, s1, 31
	s_sub_i32 s0, s0, s1
	s_bfe_i32 s1, s0, 0x80000
	s_bfe_u32 s1, s1, 0x2000d
	s_add_i32 s1, s0, s1
	s_lshl_b32 s10, s6, 2
	s_bfe_i32 s6, s1, 0x80000
	s_and_b32 s1, s1, 0xfc
	s_sub_i32 s0, s0, s1
	s_sext_i32_i16 s6, s6
	s_sext_i32_i8 s0, s0
	s_lshr_b32 s6, s6, 2
	s_add_i32 s24, s10, s0
	s_ashr_i32 s9, s7, 6
	s_ashr_i32 s25, s24, 31
	s_bfe_i64 s[10:11], s[6:7], 0x100000
	s_ashr_i32 s8, s7, 8
	s_lshl_b32 s27, s9, 10
	s_lshl_b64 s[0:1], s[24:25], 20
	s_lshl_b64 s[10:11], s[10:11], 20
	s_add_u32 s36, s78, s10
	v_lshlrev_b32_e32 v5, 5, v13
	v_bfe_i32 v15, v0, 0, 16
	v_lshlrev_b32_e32 v0, 1, v2
	v_lshrrev_b32_e32 v3, 2, v2
	s_addc_u32 s37, s79, s11
	s_add_i32 s28, s27, 0
	v_and_b32_e32 v5, 32, v5
	v_and_b32_e32 v0, 24, v0
	v_and_b32_e32 v3, 4, v3
	s_add_i32 m0, s28, 0x10000
	v_or3_b32 v0, v4, v3, v0
	v_add_lshl_u32 v3, v5, v15, 1
	global_load_lds_dwordx4 v134, s[36:37]
	s_add_i32 m0, s28, 0x12000
	v_lshl_add_u32 v146, v0, 12, v3
	s_add_u32 s10, s36, 0x80000
	global_load_lds_dwordx4 v146, s[36:37]
	s_addc_u32 s11, s37, 0
	s_add_i32 m0, s28, 0x14000
	v_lshl_add_u32 v144, v2, 12, v3
	global_load_lds_dwordx4 v134, s[10:11]
	s_add_i32 m0, s28, 0x16000
	s_add_u32 s22, s48, s0
	s_addc_u32 s23, s49, s1
	s_add_i32 s29, s28, 0x2000
	global_load_lds_dwordx4 v146, s[10:11]
	s_mov_b32 m0, s28
	s_add_u32 s0, s22, 0x80000
	global_load_lds_dwordx4 v132, s[22:23]
	s_mov_b32 m0, s29
	s_addc_u32 s1, s23, 0
	s_add_i32 s40, s28, 0x4000
	global_load_lds_dwordx4 v144, s[22:23]
	s_mov_b32 m0, s40
	s_add_i32 s41, s28, 0x6000
	global_load_lds_dwordx4 v132, s[0:1]
	s_mov_b32 m0, s41
	v_mov_b32_e32 v0, 0
	global_load_lds_dwordx4 v144, s[0:1]
	v_mov_b32_e32 v135, v0
	v_mov_b32_e32 v147, v0
	v_mov_b32_e32 v133, v0
	v_mov_b32_e32 v145, v0
	s_cmp_eq_u32 s8, 1
	s_mov_b32 s42, 0
	v_lshl_add_u64 v[8:9], s[36:37], 0, v[134:135]
	v_lshl_add_u64 v[4:5], s[36:37], 0, v[146:147]
	v_lshl_add_u64 v[2:3], s[22:23], 0, v[132:133]
	s_cselect_b64 s[0:1], -1, 0
	s_cmp_lg_u32 s8, 1
	v_lshl_add_u64 v[6:7], s[22:23], 0, v[144:145]
	s_cbranch_scc1 .LBB0_698
	s_barrier
	s_setprio 1

; #define PG8_WAIT_V(n) asm volatile("s_waitcnt vmcnt(" #n ")" ::: "memory")
; #define PG8_BAR __builtin_amdgcn_s_barrier()
; template <class Epi, bool ALIGN_EPI, class Hook = NoHook>
; __device__ __forceinline__ void gemm_phase(LAS unsigned char* lds, const Gemm g, const StaticOrder& S, const Epi& E, const Hook& HK = Hook()) {
;     ...
;     PG8_WAIT_V(0);
;     if constexpr (!ALIGN_EPI) { if (wr == 0) PG8_BAR; }
;     PG8_BAR;
; __device__ __forceinline__ void xcd_barrier(const XcdBarrier& b) {
;     asm volatile("s_waitcnt vmcnt(0)" ::: "memory");
;     __syncthreads();
;     if (threadIdx.x == 0) {
;         unsigned* bar = b.bar;
;         __builtin_amdgcn_s_waitcnt(0);
;         unsigned nloc = b.st[0], nx = b.st[1];
;         if (nloc == 0u) { xcd_barrier_complete(bar, b.x, nloc, nx); b.st[0] = nloc; b.st[1] = nx; }
.LBB0_717:
	s_setprio 0
	s_waitcnt vmcnt(0)
	s_barrier
	s_mov_b64 s[0:1], exec
	v_readlane_b32 s6, v254, 3
	v_readlane_b32 s7, v254, 4
	s_and_b64 s[6:7], s[0:1], s[6:7]
	s_mov_b64 exec, s[6:7]
	s_cbranch_execz .LBB0_770
	s_add_i32 s6, 0, 0x23ff0
	v_mov_b32_e32 v0, s6
	s_waitcnt vmcnt(0) expcnt(0) lgkmcnt(0)
	ds_read_b32 v2, v0
	s_add_i32 s6, 0, 0x23ff4
	v_mov_b32_e32 v0, s6
	ds_read_b32 v0, v0
	s_waitcnt lgkmcnt(1)
	v_cmp_ne_u32_e32 vcc, 0, v2
	s_cbranch_vccnz .LBB0_734
	v_readlane_b32 s6, v254, 0
	s_mul_i32 s28, s31, s6
	s_add_u32 s6, s62, 0xc0200
	s_addc_u32 s7, s63, 0
	s_add_u32 s8, s62, 0xc0400
	s_addc_u32 s9, s63, 0
	s_add_u32 s10, s62, 0xc0500
	s_addc_u32 s11, s63, 0
	s_add_u32 s12, s62, 0xc0600
	s_addc_u32 s13, s63, 0
	s_add_u32 s14, s62, 0xc0700
	s_addc_u32 s15, s63, 0
	s_add_u32 s16, s62, 0xc0800
	s_addc_u32 s17, s63, 0
	s_add_u32 s18, s62, 0xc0900
	s_addc_u32 s19, s63, 0
	s_add_u32 s20, s62, 0xc0a00
	s_addc_u32 s21, s63, 0
	s_add_u32 s22, s62, 0xc0b00
	s_addc_u32 s23, s63, 0
	s_add_u32 s24, s62, 0xc0c00
	s_addc_u32 s25, s63, 0
	s_add_u32 s36, s62, 0xc0d00
	s_addc_u32 s37, s63, 0
	s_add_u32 s38, s62, 0xc0e00
	s_addc_u32 s39, s63, 0
	s_add_u32 s40, s62, 0xc0f00
	s_addc_u32 s41, s63, 0
	s_add_u32 s42, s62, 0xc1000
	s_addc_u32 s43, s63, 0
	s_add_u32 s44, s62, 0xc1100
	s_addc_u32 s45, s63, 0
	s_add_u32 s78, s62, 0xc1200
	s_addc_u32 s79, s63, 0
	s_add_u32 s72, s62, 0xc1300
	s_mul_i32 s28, s28, s30
	s_addc_u32 s73, s63, 0
	s_mov_b32 s29, 1
	v_mov_b32_e32 v16, 0
	s_branch .LBB0_722
